# P2/P8 down-GEMM epilogue: first chunk of residual loads (8 dwordx4 per lane) issued before the K-loop into spare VGPRs v222-v255 so they are off the epilogue HBM burst
# speedup vs baseline: 1.0068x; 1.0035x over previous
; template <class Epi, class Sched, bool I8 = false>
; __device__ __forceinline__ void gemm_phase(LAS unsigned char* lds, const Gemm g, const Sched& S, const Epi& E) {
;     ...
; #pragma unroll
;         for (int a = 0; a < 2; ++a)
; #pragma unroll
;             for (int b = 0; b < 2; ++b)
; #pragma unroll
;                 for (int m = 0; m < 4; ++m)
; #pragma unroll
;                     for (int n = 0; n < 2; ++n) acc[a][b][m][n] = acc_t{};
;         cur = nxt; cA = nA; cB = nB; ++ui;
;     __device__ __forceinline__ void operator()(const i32x4 (&acc)[2][2][4][2], const pg8::Unit& u, int wr, int wc, int fr, int fq) const {
;     ...
;                 f32x4 pa[2][2], pb[2][2]; float rs[2];
; #pragma unroll
;                 for (int mm = 0; mm < 2; ++mm) { const int row = row0 + ai * 128 + (2 * mh + mm) * 16; rs[mm] = sh[row] * alpha;
; #pragma unroll
;                     for (int bj = 0; bj < 2; ++bj) { const size_t off = (size_t)row * DM + col0 + bj * 128; pa[mm][bj] = *(const f32x4*)(res + off); pb[mm][bj] = *(const f32x4*)(res + off + 4); } }
.LBB0_1392:
	s_add_u32 s18, s18, 0xc000
	s_addc_u32 s19, s19, 0
	s_add_u32 s47, s20, 0x10000
	v_mov_b32_e32 v2, 0
	s_addc_u32 s48, s21, 0
	s_mov_b32 s49, -2
	s_waitcnt lgkmcnt(0)
	v_mov_b32_e32 v3, v2
	v_mov_b32_e32 v4, v2
	v_mov_b32_e32 v5, v2
	v_mov_b32_e32 v6, v2
	v_mov_b32_e32 v7, v2
	v_mov_b32_e32 v8, v2
	v_mov_b32_e32 v9, v2
	v_mov_b32_e32 v18, v2
	v_mov_b32_e32 v19, v2
	v_mov_b32_e32 v20, v2
	v_mov_b32_e32 v21, v2
	v_mov_b32_e32 v22, v2
	v_mov_b32_e32 v23, v2
	v_mov_b32_e32 v24, v2
	v_mov_b32_e32 v25, v2
	v_mov_b32_e32 v34, v2
	v_mov_b32_e32 v35, v2
	v_mov_b32_e32 v36, v2
	v_mov_b32_e32 v37, v2
	v_mov_b32_e32 v38, v2
	v_mov_b32_e32 v39, v2
	v_mov_b32_e32 v40, v2
	v_mov_b32_e32 v41, v2
	v_mov_b32_e32 v50, v2
	v_mov_b32_e32 v51, v2
	v_mov_b32_e32 v52, v2
	v_mov_b32_e32 v53, v2
	v_mov_b32_e32 v54, v2
	v_mov_b32_e32 v55, v2
	v_mov_b32_e32 v56, v2
	v_mov_b32_e32 v57, v2
	v_mov_b32_e32 v10, v2
	v_mov_b32_e32 v11, v2
	v_mov_b32_e32 v12, v2
	v_mov_b32_e32 v13, v2
	v_mov_b32_e32 v14, v2
	v_mov_b32_e32 v15, v2
	v_mov_b32_e32 v16, v2
	v_mov_b32_e32 v17, v2
	v_mov_b32_e32 v26, v2
	v_mov_b32_e32 v27, v2
	v_mov_b32_e32 v28, v2
	v_mov_b32_e32 v29, v2
	v_mov_b32_e32 v30, v2
	v_mov_b32_e32 v31, v2
	v_mov_b32_e32 v32, v2
	v_mov_b32_e32 v33, v2
	v_mov_b32_e32 v42, v2
	v_mov_b32_e32 v43, v2
	v_mov_b32_e32 v44, v2
	v_mov_b32_e32 v45, v2
	v_mov_b32_e32 v46, v2
	v_mov_b32_e32 v47, v2
	v_mov_b32_e32 v48, v2
	v_mov_b32_e32 v49, v2
	v_mov_b32_e32 v58, v2
	v_mov_b32_e32 v59, v2
	v_mov_b32_e32 v60, v2
	v_mov_b32_e32 v61, v2
	v_mov_b32_e32 v62, v2
	v_mov_b32_e32 v63, v2
	v_mov_b32_e32 v64, v2
	v_mov_b32_e32 v65, v2
	v_mov_b32_e32 v82, v2
	v_mov_b32_e32 v83, v2
	v_mov_b32_e32 v84, v2
	v_mov_b32_e32 v85, v2
	v_mov_b32_e32 v86, v2
	v_mov_b32_e32 v87, v2
	v_mov_b32_e32 v88, v2
	v_mov_b32_e32 v89, v2
	v_mov_b32_e32 v98, v2
	v_mov_b32_e32 v99, v2
	v_mov_b32_e32 v100, v2
	v_mov_b32_e32 v101, v2
	v_mov_b32_e32 v102, v2
	v_mov_b32_e32 v103, v2
	v_mov_b32_e32 v104, v2
	v_mov_b32_e32 v105, v2
	v_mov_b32_e32 v114, v2
	v_mov_b32_e32 v115, v2
	v_mov_b32_e32 v116, v2
	v_mov_b32_e32 v117, v2
	v_mov_b32_e32 v118, v2
	v_mov_b32_e32 v119, v2
	v_mov_b32_e32 v120, v2
	v_mov_b32_e32 v121, v2
	v_mov_b32_e32 v130, v2
	v_mov_b32_e32 v131, v2
	v_mov_b32_e32 v132, v2
	v_mov_b32_e32 v133, v2
	v_mov_b32_e32 v134, v2
	v_mov_b32_e32 v135, v2
	v_mov_b32_e32 v136, v2
	v_mov_b32_e32 v137, v2
	v_mov_b32_e32 v90, v2
	v_mov_b32_e32 v91, v2
	v_mov_b32_e32 v92, v2
	v_mov_b32_e32 v93, v2
	v_mov_b32_e32 v94, v2
	v_mov_b32_e32 v95, v2
	v_mov_b32_e32 v96, v2
	v_mov_b32_e32 v97, v2
	v_mov_b32_e32 v106, v2
	v_mov_b32_e32 v107, v2
	v_mov_b32_e32 v108, v2
	v_mov_b32_e32 v109, v2
	v_mov_b32_e32 v110, v2
	v_mov_b32_e32 v111, v2
	v_mov_b32_e32 v112, v2
	v_mov_b32_e32 v113, v2
	v_mov_b32_e32 v122, v2
	v_mov_b32_e32 v123, v2
	v_mov_b32_e32 v124, v2
	v_mov_b32_e32 v125, v2
	v_mov_b32_e32 v126, v2
	v_mov_b32_e32 v127, v2
	v_mov_b32_e32 v128, v2
	v_mov_b32_e32 v129, v2
	v_mov_b32_e32 v138, v2
	v_mov_b32_e32 v139, v2
	v_mov_b32_e32 v140, v2
	v_mov_b32_e32 v141, v2
	v_mov_b32_e32 v142, v2
	v_mov_b32_e32 v143, v2
	v_mov_b32_e32 v144, v2
	v_mov_b32_e32 v145, v2
	v_lshl_add_u32 v252, s45, 8, v1
	v_lshl_or_b32 v253, s46, 8, v179
	v_lshlrev_b32_e32 v252, 14, v252
	v_lshl_add_u32 v252, v253, 2, v252
	v_mov_b32_e32 v253, 0
	v_lshl_add_u64 v[252:253], v[252:253], 0, v[154:155]
	v_mov_b32_e32 v248, 0x40000
	v_mov_b32_e32 v249, 0
	v_lshl_add_u64 v[248:249], v[248:249], 0, v[252:253]
	global_load_dwordx4 v[222:225], v[252:253], off nt
	global_load_dwordx4 v[226:229], v[252:253], off offset:16 nt
	global_load_dwordx4 v[230:233], v[252:253], off offset:512 nt
	global_load_dwordx4 v[234:237], v[248:249], off offset:16 nt
	global_load_dwordx4 v[238:241], v[248:249], off nt
	global_load_dwordx4 v[242:245], v[248:249], off offset:528 nt
	s_nop 0
	global_load_dwordx4 v[252:255], v[252:253], off offset:528 nt
	s_nop 0
	global_load_dwordx4 v[248:251], v[248:249], off offset:512 nt

;     __device__ __forceinline__ void operator()(const i32x4 (&acc)[2][2][4][2], const pg8::Unit& u, int wr, int wc, int fr, int fq) const {
;         int row0 = u.pm * 256 + wr * 64 + fr, col0 = u.pn * 256 + wc * 32 + 8 * fq;
;         asm volatile("" : "+v"(row0), "+v"(col0));
;         f32x4 s0[2], s1[2];
; #pragma unroll
;         for (int bj = 0; bj < 2; ++bj) { s0[bj] = *(const f32x4*)(sbn + col0 + bj * 128); s1[bj] = *(const f32x4*)(sbn + col0 + bj * 128 + 4); }
; #pragma unroll
;         for (int ai = 0; ai < 2; ++ai)
; #pragma unroll
;             for (int mh = 0; mh < 2; ++mh) {
;                 f32x4 pa[2][2], pb[2][2]; float rs[2];
; #pragma unroll
;                 for (int mm = 0; mm < 2; ++mm) { const int row = row0 + ai * 128 + (2 * mh + mm) * 16; rs[mm] = sh[row] * alpha;
; #pragma unroll
;                     for (int bj = 0; bj < 2; ++bj) { const size_t off = (size_t)row * DM + col0 + bj * 128; pa[mm][bj] = *(const f32x4*)(res + off); pb[mm][bj] = *(const f32x4*)(res + off + 4); } }
; #pragma unroll
;                 for (int mm = 0; mm < 2; ++mm) {
;                     const int m = 2 * mh + mm, row = row0 + ai * 128 + m * 16; float ss = 0.f;
; #pragma unroll
;                     for (int bj = 0; bj < 2; ++bj) {
;                         const size_t off = (size_t)row * DM + col0 + bj * 128; f32x4 v0, v1;
; #pragma unroll
;                         for (int e = 0; e < 4; ++e) { v0[e] = pa[mm][bj][e] + (float)acc[ai][bj][m][0][e] * rs[mm] * s0[bj][e]; v1[e] = pb[mm][bj][e] + (float)acc[ai][bj][m][1][e] * rs[mm] * s1[bj][e]; }
;                         if (out) { *(f32x4*)(out + off) = v0; *(f32x4*)(out + off + 4) = v1; }
;                         if (ob) { u32x4 w; w.x = cvt_pk_bf16(v0[0], v0[1]); w.y = cvt_pk_bf16(v0[2], v0[3]); w.z = cvt_pk_bf16(v1[0], v1[1]); w.w = cvt_pk_bf16(v1[2], v1[3]); *(u32x4*)(ob + blk_off(row, col0 + bj * 128, KT4)) = w; }
;                         ss += (v0[0] * v0[0] + v0[1] * v0[1]) + (v0[2] * v0[2] + v0[3] * v0[3]) + (v1[0] * v1[0] + v1[1] * v1[1]) + (v1[2] * v1[2] + v1[3] * v1[3]);
;                     }
;                     ss += __shfl_xor(ss, 16); ss += __shfl_xor(ss, 32);
;                     if (fq == 0 && racc) atomicAdd(racc + row, (u64)(ss * 4294967296.0f));
.LBB0_1396:
	v_lshl_add_u32 v176, s45, 8, v1
	v_lshl_or_b32 v206, s46, 8, v179
	v_cvt_f32_i32_e32 v217, v134
	v_ashrrev_i32_e32 v177, 31, v176
	v_lshl_add_u64 v[66:67], v[176:177], 2, s[8:9]
	v_ashrrev_i32_e32 v207, 31, v206
	global_load_dword v185, v[66:67], off
	v_lshlrev_b64 v[66:67], 2, v[206:207]
	v_lshl_add_u64 v[70:71], s[10:11], 0, v[66:67]
	global_load_dwordx4 v[74:77], v[70:71], off offset:16 nt
	global_load_dwordx4 v[78:81], v[70:71], off nt
	v_lshlrev_b64 v[68:69], 14, v[176:177]
	v_lshl_add_u64 v[174:175], v[154:155], 0, v[66:67]
	v_lshl_add_u64 v[146:147], v[174:175], 0, v[68:69]
	global_load_dwordx4 v[66:69], v[70:71], off offset:528 nt
	s_nop 0
	global_load_dwordx4 v[70:73], v[70:71], off offset:512 nt
	s_nop 0
	v_add_u32_e32 v134, 16, v176
	v_cvt_f32_i32_e32 v214, v140
	v_cvt_f32_i32_e32 v219, v135
	v_lshlrev_b32_e32 v140, 7, v176
	v_ashrrev_i32_e32 v135, 31, v134
	v_cvt_f32_i32_e32 v205, v138
	v_cvt_f32_i32_e32 v212, v139
	v_cvt_f32_i32_e32 v216, v141
	v_and_b32_e32 v138, 63, v206
	v_ashrrev_i32_e32 v139, 2, v176
	v_and_b32_e32 v208, 0x7f80, v140
	v_lshlrev_b64 v[140:141], 14, v[134:135]
	v_cvt_f32_i32_e32 v204, v142
	v_cvt_f32_i32_e32 v207, v143
	v_and_b32_e32 v220, 0xffffffc0, v139
	v_lshlrev_b32_e32 v164, 1, v138
	v_lshl_add_u64 v[138:139], v[134:135], 2, s[8:9]
	v_lshl_add_u64 v[142:143], v[174:175], 0, v[140:141]
	v_cvt_f32_i32_e32 v213, v144
	v_cvt_f32_i32_e32 v215, v145
	global_load_dword v184, v[138:139], off
	s_nop 0
	s_nop 0
	v_cvt_f32_i32_e32 v218, v130
	v_ashrrev_i32_e32 v130, 6, v206
	v_add_u32_e32 v202, v220, v130
	v_ashrrev_i32_e32 v203, 31, v202
	v_lshlrev_b64 v[202:203], 15, v[202:203]
	v_mov_b32_e32 v209, v165
	v_lshl_add_u64 v[202:203], s[72:73], 0, v[202:203]
	v_lshl_add_u64 v[202:203], v[202:203], 0, v[208:209]
	v_lshl_add_u64 v[210:211], v[202:203], 0, v[164:165]
	v_cvt_f32_i32_e32 v137, v137
	v_cvt_f32_i32_e32 v131, v131
	v_cvt_f32_i32_e32 v136, v136
	v_cvt_f32_i32_e32 v132, v132
	v_cvt_f32_i32_e32 v133, v133
	s_waitcnt vmcnt(0)
	v_mov_b32_e32 v186, v222
	v_mov_b32_e32 v187, v223
	v_mov_b32_e32 v188, v224
	v_mov_b32_e32 v189, v225
	v_mov_b32_e32 v190, v226
	v_mov_b32_e32 v191, v227
	v_mov_b32_e32 v192, v228
	v_mov_b32_e32 v193, v229
	v_mov_b32_e32 v194, v230
	v_mov_b32_e32 v195, v231
	v_mov_b32_e32 v196, v232
	v_mov_b32_e32 v197, v233
	v_mov_b32_e32 v198, v252
	v_mov_b32_e32 v199, v253
	v_mov_b32_e32 v200, v254
	v_mov_b32_e32 v201, v255
	v_mov_b32_e32 v146, v234
	v_mov_b32_e32 v147, v235
	v_mov_b32_e32 v148, v236
	v_mov_b32_e32 v149, v237
	v_mov_b32_e32 v150, v238
	v_mov_b32_e32 v151, v239
	v_mov_b32_e32 v152, v240
	v_mov_b32_e32 v153, v241
	v_mov_b32_e32 v138, v242
	v_mov_b32_e32 v139, v243
	v_mov_b32_e32 v140, v244
	v_mov_b32_e32 v141, v245
	v_mov_b32_e32 v142, v248
	v_mov_b32_e32 v143, v249
	v_mov_b32_e32 v144, v250
	v_mov_b32_e32 v145, v251
	v_mul_f32_e32 v185, 0.5, v185
	v_mul_f32_e32 v202, v185, v204
	v_mul_f32_e32 v204, v185, v207
	v_mul_f32_e32 v207, v185, v213
	v_mul_f32_e32 v213, v185, v215
	v_mul_f32_e32 v203, v185, v205
	v_mul_f32_e32 v205, v185, v212
	v_fma_f32 v187, v79, v204, v187
	v_fmac_f32_e32 v189, v81, v213
	v_mul_f32_e32 v212, v185, v214
	v_mul_f32_e32 v214, v185, v216
	v_fma_f32 v186, v78, v202, v186
	v_fma_f32 v190, v74, v203, v190
	v_fma_f32 v191, v75, v205, v191
	v_fma_f32 v188, v80, v207, v188
	v_cvt_pk_bf16_f32 v202, v186, v187
	v_cvt_pk_bf16_f32 v203, v188, v189
	v_mul_f32_e32 v187, v187, v187
	v_mul_f32_e32 v189, v189, v189
	v_fmac_f32_e32 v193, v77, v214
	v_cvt_pk_bf16_f32 v204, v190, v191
	v_mul_f32_e32 v191, v191, v191
	v_fmac_f32_e32 v187, v186, v186
	v_fmac_f32_e32 v189, v188, v188
	v_fma_f32 v192, v76, v212, v192
	v_cvt_pk_bf16_f32 v205, v192, v193
	v_mul_f32_e32 v193, v193, v193
	v_fmac_f32_e32 v191, v190, v190
	v_add_f32_e32 v186, v187, v189
	v_fmac_f32_e32 v193, v192, v192
	v_add_f32_e32 v186, v191, v186
	v_add_f32_e32 v190, v193, v186
	v_mul_f32_e32 v186, v185, v219
	v_mul_f32_e32 v137, v185, v137
	v_mul_f32_e32 v215, v185, v217
	v_fma_f32 v191, v71, v186, v195
	v_mul_f32_e32 v131, v185, v131
	v_mul_f32_e32 v136, v185, v136
	v_fmac_f32_e32 v197, v73, v137
	v_mul_f32_e32 v216, v185, v218
	v_fma_f32 v194, v70, v215, v194
	v_fma_f32 v131, v67, v131, v199
	v_fma_f32 v136, v72, v136, v196
	v_mul_f32_e32 v132, v185, v132
	v_mul_f32_e32 v133, v185, v133
	v_mul_f32_e32 v137, v191, v191
	v_mul_f32_e32 v185, v197, v197
	v_fma_f32 v198, v66, v216, v198
	global_store_dwordx4 v[210:211], v[202:205], off
	v_cvt_pk_bf16_f32 v186, v194, v191
	v_cvt_pk_bf16_f32 v187, v136, v197
	v_cvt_pk_bf16_f32 v188, v198, v131
	v_fmac_f32_e32 v137, v194, v194
	v_fmac_f32_e32 v185, v136, v136
	v_mul_f32_e32 v131, v131, v131
	v_fmac_f32_e32 v201, v69, v133
	v_add_f32_e32 v136, v137, v185
	v_fmac_f32_e32 v131, v198, v198
	v_fma_f32 v132, v68, v132, v200
	v_add_f32_e32 v131, v136, v131
	v_mul_f32_e32 v136, v201, v201
	v_fmac_f32_e32 v136, v132, v132
	v_cvt_pk_bf16_f32 v189, v132, v201
	v_add_f32_e32 v131, v136, v131
	v_and_b32_e32 v132, 64, v183
	v_add_f32_e32 v185, v190, v131
	v_xor_b32_e32 v131, 16, v183
	v_add_u32_e32 v192, 64, v132
	v_cmp_lt_i32_e32 vcc, v131, v192
	v_add_u32_e32 v133, 0x80, v206
	s_nop 0
	v_cndmask_b32_e32 v131, v183, v131, vcc
	v_lshlrev_b32_e32 v132, 2, v131
	ds_bpermute_b32 v193, v132, v185
	v_ashrrev_i32_e32 v131, 6, v133
	v_xor_b32_e32 v133, 32, v183
	v_add_u32_e32 v136, v131, v220
	v_cmp_lt_i32_e32 vcc, v133, v192
	v_ashrrev_i32_e32 v137, 31, v136
	v_lshlrev_b64 v[190:191], 15, v[136:137]
	v_cndmask_b32_e32 v133, v183, v133, vcc
	s_waitcnt lgkmcnt(0)
	v_add_f32_e32 v136, v185, v193
	v_lshlrev_b32_e32 v133, 2, v133
	ds_bpermute_b32 v137, v133, v136
	v_lshl_add_u64 v[190:191], s[72:73], 0, v[190:191]
	v_lshl_add_u64 v[190:191], v[190:191], 0, v[208:209]
	v_lshl_add_u64 v[190:191], v[190:191], 0, v[164:165]
	global_store_dwordx4 v[190:191], v[186:189], off
	s_and_saveexec_b64 s[18:19], s[2:3]
	s_cbranch_execz .LBB0_1398
	s_waitcnt lgkmcnt(0)
	v_add_f32_e32 v136, v136, v137
	v_mul_f32_e32 v136, 0x4f800000, v136
	v_trunc_f32_e32 v136, v136
	v_mul_f32_e32 v137, 0x2f800000, v136
	v_floor_f32_e32 v137, v137
	v_fmac_f32_e32 v136, 0xcf800000, v137
	v_cvt_u32_f32_e32 v136, v136
	v_cvt_u32_f32_e32 v137, v137
	v_lshl_add_u64 v[186:187], v[176:177], 3, s[12:13]
	global_atomic_add_x2 v[186:187], v[136:137], off

; template <class Epi, class Sched, bool I8 = false>
; __device__ __forceinline__ void gemm_phase(LAS unsigned char* lds, const Gemm g, const Sched& S, const Epi& E) {
;     ...
; #pragma unroll
;         for (int a = 0; a < 2; ++a)
; #pragma unroll
;             for (int b = 0; b < 2; ++b)
; #pragma unroll
;                 for (int m = 0; m < 4; ++m)
; #pragma unroll
;                     for (int n = 0; n < 2; ++n) acc[a][b][m][n] = acc_t{};
;         cur = nxt; cA = nA; cB = nB; ++ui;
;     __device__ __forceinline__ void operator()(const i32x4 (&acc)[2][2][4][2], const pg8::Unit& u, int wr, int wc, int fr, int fq) const {
;     ...
;                 f32x4 pa[2][2], pb[2][2]; float rs[2];
; #pragma unroll
;                 for (int mm = 0; mm < 2; ++mm) { const int row = row0 + ai * 128 + (2 * mh + mm) * 16; rs[mm] = sh[row] * alpha;
; #pragma unroll
;                     for (int bj = 0; bj < 2; ++bj) { const size_t off = (size_t)row * DM + col0 + bj * 128; pa[mm][bj] = *(const f32x4*)(res + off); pb[mm][bj] = *(const f32x4*)(res + off + 4); } }
.LBB0_4167:
	s_add_u32 s20, s20, 0xc000
	s_addc_u32 s21, s21, 0
	s_add_u32 s49, s22, 0x10000
	v_mov_b32_e32 v2, 0
	s_addc_u32 s50, s23, 0
	s_mov_b32 s51, -2
	s_waitcnt lgkmcnt(0)
	v_mov_b32_e32 v3, v2
	v_mov_b32_e32 v4, v2
	v_mov_b32_e32 v5, v2
	v_mov_b32_e32 v6, v2
	v_mov_b32_e32 v7, v2
	v_mov_b32_e32 v8, v2
	v_mov_b32_e32 v9, v2
	v_mov_b32_e32 v18, v2
	v_mov_b32_e32 v19, v2
	v_mov_b32_e32 v20, v2
	v_mov_b32_e32 v21, v2
	v_mov_b32_e32 v22, v2
	v_mov_b32_e32 v23, v2
	v_mov_b32_e32 v24, v2
	v_mov_b32_e32 v25, v2
	v_mov_b32_e32 v34, v2
	v_mov_b32_e32 v35, v2
	v_mov_b32_e32 v36, v2
	v_mov_b32_e32 v37, v2
	v_mov_b32_e32 v38, v2
	v_mov_b32_e32 v39, v2
	v_mov_b32_e32 v40, v2
	v_mov_b32_e32 v41, v2
	v_mov_b32_e32 v50, v2
	v_mov_b32_e32 v51, v2
	v_mov_b32_e32 v52, v2
	v_mov_b32_e32 v53, v2
	v_mov_b32_e32 v54, v2
	v_mov_b32_e32 v55, v2
	v_mov_b32_e32 v56, v2
	v_mov_b32_e32 v57, v2
	v_mov_b32_e32 v10, v2
	v_mov_b32_e32 v11, v2
	v_mov_b32_e32 v12, v2
	v_mov_b32_e32 v13, v2
	v_mov_b32_e32 v14, v2
	v_mov_b32_e32 v15, v2
	v_mov_b32_e32 v16, v2
	v_mov_b32_e32 v17, v2
	v_mov_b32_e32 v26, v2
	v_mov_b32_e32 v27, v2
	v_mov_b32_e32 v28, v2
	v_mov_b32_e32 v29, v2
	v_mov_b32_e32 v30, v2
	v_mov_b32_e32 v31, v2
	v_mov_b32_e32 v32, v2
	v_mov_b32_e32 v33, v2
	v_mov_b32_e32 v42, v2
	v_mov_b32_e32 v43, v2
	v_mov_b32_e32 v44, v2
	v_mov_b32_e32 v45, v2
	v_mov_b32_e32 v46, v2
	v_mov_b32_e32 v47, v2
	v_mov_b32_e32 v48, v2
	v_mov_b32_e32 v49, v2
	v_mov_b32_e32 v58, v2
	v_mov_b32_e32 v59, v2
	v_mov_b32_e32 v60, v2
	v_mov_b32_e32 v61, v2
	v_mov_b32_e32 v62, v2
	v_mov_b32_e32 v63, v2
	v_mov_b32_e32 v64, v2
	v_mov_b32_e32 v65, v2
	v_mov_b32_e32 v82, v2
	v_mov_b32_e32 v83, v2
	v_mov_b32_e32 v84, v2
	v_mov_b32_e32 v85, v2
	v_mov_b32_e32 v86, v2
	v_mov_b32_e32 v87, v2
	v_mov_b32_e32 v88, v2
	v_mov_b32_e32 v89, v2
	v_mov_b32_e32 v98, v2
	v_mov_b32_e32 v99, v2
	v_mov_b32_e32 v100, v2
	v_mov_b32_e32 v101, v2
	v_mov_b32_e32 v102, v2
	v_mov_b32_e32 v103, v2
	v_mov_b32_e32 v104, v2
	v_mov_b32_e32 v105, v2
	v_mov_b32_e32 v114, v2
	v_mov_b32_e32 v115, v2
	v_mov_b32_e32 v116, v2
	v_mov_b32_e32 v117, v2
	v_mov_b32_e32 v118, v2
	v_mov_b32_e32 v119, v2
	v_mov_b32_e32 v120, v2
	v_mov_b32_e32 v121, v2
	v_mov_b32_e32 v130, v2
	v_mov_b32_e32 v131, v2
	v_mov_b32_e32 v132, v2
	v_mov_b32_e32 v133, v2
	v_mov_b32_e32 v134, v2
	v_mov_b32_e32 v135, v2
	v_mov_b32_e32 v136, v2
	v_mov_b32_e32 v137, v2
	v_mov_b32_e32 v90, v2
	v_mov_b32_e32 v91, v2
	v_mov_b32_e32 v92, v2
	v_mov_b32_e32 v93, v2
	v_mov_b32_e32 v94, v2
	v_mov_b32_e32 v95, v2
	v_mov_b32_e32 v96, v2
	v_mov_b32_e32 v97, v2
	v_mov_b32_e32 v106, v2
	v_mov_b32_e32 v107, v2
	v_mov_b32_e32 v108, v2
	v_mov_b32_e32 v109, v2
	v_mov_b32_e32 v110, v2
	v_mov_b32_e32 v111, v2
	v_mov_b32_e32 v112, v2
	v_mov_b32_e32 v113, v2
	v_mov_b32_e32 v122, v2
	v_mov_b32_e32 v123, v2
	v_mov_b32_e32 v124, v2
	v_mov_b32_e32 v125, v2
	v_mov_b32_e32 v126, v2
	v_mov_b32_e32 v127, v2
	v_mov_b32_e32 v128, v2
	v_mov_b32_e32 v129, v2
	v_mov_b32_e32 v138, v2
	v_mov_b32_e32 v139, v2
	v_mov_b32_e32 v140, v2
	v_mov_b32_e32 v141, v2
	v_mov_b32_e32 v142, v2
	v_mov_b32_e32 v143, v2
	v_mov_b32_e32 v144, v2
	v_mov_b32_e32 v145, v2
	v_lshl_add_u32 v252, s47, 8, v1
	v_lshl_or_b32 v253, s48, 8, v177
	v_lshlrev_b32_e32 v252, 14, v252
	v_lshl_add_u32 v252, v253, 2, v252
	v_mov_b32_e32 v253, 0
	v_lshl_add_u64 v[252:253], v[252:253], 0, s[76:77]
	v_mov_b32_e32 v248, 0x40000
	v_mov_b32_e32 v249, 0
	v_lshl_add_u64 v[248:249], v[248:249], 0, v[252:253]
	global_load_dwordx4 v[222:225], v[252:253], off nt
	global_load_dwordx4 v[226:229], v[252:253], off offset:16 nt
	global_load_dwordx4 v[230:233], v[252:253], off offset:512 nt
	global_load_dwordx4 v[234:237], v[248:249], off offset:16 nt
	global_load_dwordx4 v[238:241], v[248:249], off nt
	global_load_dwordx4 v[242:245], v[248:249], off offset:528 nt
	s_nop 0
	global_load_dwordx4 v[252:255], v[252:253], off offset:528 nt
	s_nop 0
	global_load_dwordx4 v[248:251], v[248:249], off offset:512 nt

;     __device__ __forceinline__ void operator()(const i32x4 (&acc)[2][2][4][2], const pg8::Unit& u, int wr, int wc, int fr, int fq) const {
;         int row0 = u.pm * 256 + wr * 64 + fr, col0 = u.pn * 256 + wc * 32 + 8 * fq;
;         asm volatile("" : "+v"(row0), "+v"(col0));
;         f32x4 s0[2], s1[2];
; #pragma unroll
;         for (int bj = 0; bj < 2; ++bj) { s0[bj] = *(const f32x4*)(sbn + col0 + bj * 128); s1[bj] = *(const f32x4*)(sbn + col0 + bj * 128 + 4); }
; #pragma unroll
;         for (int ai = 0; ai < 2; ++ai)
; #pragma unroll
;             for (int mh = 0; mh < 2; ++mh) {
;                 f32x4 pa[2][2], pb[2][2]; float rs[2];
; #pragma unroll
;                 for (int mm = 0; mm < 2; ++mm) { const int row = row0 + ai * 128 + (2 * mh + mm) * 16; rs[mm] = sh[row] * alpha;
; #pragma unroll
;                     for (int bj = 0; bj < 2; ++bj) { const size_t off = (size_t)row * DM + col0 + bj * 128; pa[mm][bj] = *(const f32x4*)(res + off); pb[mm][bj] = *(const f32x4*)(res + off + 4); } }
; #pragma unroll
;                 for (int mm = 0; mm < 2; ++mm) {
;                     const int m = 2 * mh + mm, row = row0 + ai * 128 + m * 16; float ss = 0.f;
; #pragma unroll
;                     for (int bj = 0; bj < 2; ++bj) {
;                         const size_t off = (size_t)row * DM + col0 + bj * 128; f32x4 v0, v1;
; #pragma unroll
;                         for (int e = 0; e < 4; ++e) { v0[e] = pa[mm][bj][e] + (float)acc[ai][bj][m][0][e] * rs[mm] * s0[bj][e]; v1[e] = pb[mm][bj][e] + (float)acc[ai][bj][m][1][e] * rs[mm] * s1[bj][e]; }
;                         if (out) { *(f32x4*)(out + off) = v0; *(f32x4*)(out + off + 4) = v1; }
;                         if (ob) { u32x4 w; w.x = cvt_pk_bf16(v0[0], v0[1]); w.y = cvt_pk_bf16(v0[2], v0[3]); w.z = cvt_pk_bf16(v1[0], v1[1]); w.w = cvt_pk_bf16(v1[2], v1[3]); *(u32x4*)(ob + blk_off(row, col0 + bj * 128, KT4)) = w; }
;                         ss += (v0[0] * v0[0] + v0[1] * v0[1]) + (v0[2] * v0[2] + v0[3] * v0[3]) + (v1[0] * v1[0] + v1[1] * v1[1]) + (v1[2] * v1[2] + v1[3] * v1[3]);
;                     }
;                     ss += __shfl_xor(ss, 16); ss += __shfl_xor(ss, 32);
;                     if (fq == 0 && racc) atomicAdd(racc + row, (u64)(ss * 4294967296.0f));
.LBB0_4171:
	v_lshl_add_u32 v174, s47, 8, v1
	v_lshl_or_b32 v204, s48, 8, v177
	v_cvt_f32_i32_e32 v215, v134
	v_ashrrev_i32_e32 v175, 31, v174
	v_lshl_add_u64 v[66:67], v[174:175], 2, s[8:9]
	v_ashrrev_i32_e32 v205, 31, v204
	global_load_dword v183, v[66:67], off
	v_lshlrev_b64 v[66:67], 2, v[204:205]
	v_lshl_add_u64 v[70:71], s[10:11], 0, v[66:67]
	global_load_dwordx4 v[74:77], v[70:71], off offset:16 nt
	global_load_dwordx4 v[78:81], v[70:71], off nt
	v_lshlrev_b64 v[68:69], 14, v[174:175]
	v_lshl_add_u64 v[172:173], s[76:77], 0, v[66:67]
	v_lshl_add_u64 v[146:147], v[172:173], 0, v[68:69]
	global_load_dwordx4 v[66:69], v[70:71], off offset:528 nt
	s_nop 0
	global_load_dwordx4 v[70:73], v[70:71], off offset:512 nt
	s_nop 0
	v_add_u32_e32 v134, 16, v174
	v_cvt_f32_i32_e32 v212, v140
	v_cvt_f32_i32_e32 v217, v135
	v_lshlrev_b32_e32 v140, 7, v174
	v_ashrrev_i32_e32 v135, 31, v134
	v_cvt_f32_i32_e32 v203, v138
	v_cvt_f32_i32_e32 v210, v139
	v_cvt_f32_i32_e32 v214, v141
	v_and_b32_e32 v138, 63, v204
	v_ashrrev_i32_e32 v139, 2, v174
	v_and_b32_e32 v206, 0x7f80, v140
	v_lshlrev_b64 v[140:141], 14, v[134:135]
	v_cvt_f32_i32_e32 v202, v142
	v_cvt_f32_i32_e32 v205, v143
	v_and_b32_e32 v218, 0xffffffc0, v139
	v_lshlrev_b32_e32 v162, 1, v138
	v_lshl_add_u64 v[138:139], v[134:135], 2, s[8:9]
	v_lshl_add_u64 v[142:143], v[172:173], 0, v[140:141]
	v_cvt_f32_i32_e32 v211, v144
	v_cvt_f32_i32_e32 v213, v145
	global_load_dword v182, v[138:139], off
	s_nop 0
	s_nop 0
	v_cvt_f32_i32_e32 v216, v130
	v_ashrrev_i32_e32 v130, 6, v204
	v_add_u32_e32 v200, v218, v130
	v_ashrrev_i32_e32 v201, 31, v200
	v_lshlrev_b64 v[200:201], 15, v[200:201]
	v_mov_b32_e32 v207, v163
	v_lshl_add_u64 v[200:201], s[72:73], 0, v[200:201]
	v_lshl_add_u64 v[200:201], v[200:201], 0, v[206:207]
	v_lshl_add_u64 v[208:209], v[200:201], 0, v[162:163]
	v_cvt_f32_i32_e32 v137, v137
	v_cvt_f32_i32_e32 v131, v131
	v_cvt_f32_i32_e32 v136, v136
	v_cvt_f32_i32_e32 v132, v132
	v_cvt_f32_i32_e32 v133, v133
	s_waitcnt vmcnt(0)
	v_mov_b32_e32 v184, v222
	v_mov_b32_e32 v185, v223
	v_mov_b32_e32 v186, v224
	v_mov_b32_e32 v187, v225
	v_mov_b32_e32 v188, v226
	v_mov_b32_e32 v189, v227
	v_mov_b32_e32 v190, v228
	v_mov_b32_e32 v191, v229
	v_mov_b32_e32 v192, v230
	v_mov_b32_e32 v193, v231
	v_mov_b32_e32 v194, v232
	v_mov_b32_e32 v195, v233
	v_mov_b32_e32 v196, v252
	v_mov_b32_e32 v197, v253
	v_mov_b32_e32 v198, v254
	v_mov_b32_e32 v199, v255
	v_mov_b32_e32 v146, v234
	v_mov_b32_e32 v147, v235
	v_mov_b32_e32 v148, v236
	v_mov_b32_e32 v149, v237
	v_mov_b32_e32 v150, v238
	v_mov_b32_e32 v151, v239
	v_mov_b32_e32 v152, v240
	v_mov_b32_e32 v153, v241
	v_mov_b32_e32 v138, v242
	v_mov_b32_e32 v139, v243
	v_mov_b32_e32 v140, v244
	v_mov_b32_e32 v141, v245
	v_mov_b32_e32 v142, v248
	v_mov_b32_e32 v143, v249
	v_mov_b32_e32 v144, v250
	v_mov_b32_e32 v145, v251
	v_mul_f32_e32 v183, 0.5, v183
	v_mul_f32_e32 v200, v183, v202
	v_mul_f32_e32 v202, v183, v205
	v_mul_f32_e32 v205, v183, v211
	v_mul_f32_e32 v211, v183, v213
	v_mul_f32_e32 v201, v183, v203
	v_mul_f32_e32 v203, v183, v210
	v_fma_f32 v185, v79, v202, v185
	v_fmac_f32_e32 v187, v81, v211
	v_mul_f32_e32 v210, v183, v212
	v_mul_f32_e32 v212, v183, v214
	v_fma_f32 v184, v78, v200, v184
	v_fma_f32 v188, v74, v201, v188
	v_fma_f32 v189, v75, v203, v189
	v_fma_f32 v186, v80, v205, v186
	v_cvt_pk_bf16_f32 v200, v184, v185
	v_cvt_pk_bf16_f32 v201, v186, v187
	v_mul_f32_e32 v185, v185, v185
	v_mul_f32_e32 v187, v187, v187
	v_fmac_f32_e32 v191, v77, v212
	v_cvt_pk_bf16_f32 v202, v188, v189
	v_mul_f32_e32 v189, v189, v189
	v_fmac_f32_e32 v185, v184, v184
	v_fmac_f32_e32 v187, v186, v186
	v_fma_f32 v190, v76, v210, v190
	v_cvt_pk_bf16_f32 v203, v190, v191
	v_mul_f32_e32 v191, v191, v191
	v_fmac_f32_e32 v189, v188, v188
	v_add_f32_e32 v184, v185, v187
	v_fmac_f32_e32 v191, v190, v190
	v_add_f32_e32 v184, v189, v184
	v_add_f32_e32 v188, v191, v184
	v_mul_f32_e32 v184, v183, v217
	v_mul_f32_e32 v137, v183, v137
	v_mul_f32_e32 v213, v183, v215
	v_fma_f32 v189, v71, v184, v193
	v_mul_f32_e32 v131, v183, v131
	v_mul_f32_e32 v136, v183, v136
	v_fmac_f32_e32 v195, v73, v137
	v_mul_f32_e32 v214, v183, v216
	v_fma_f32 v192, v70, v213, v192
	v_fma_f32 v131, v67, v131, v197
	v_fma_f32 v136, v72, v136, v194
	v_mul_f32_e32 v132, v183, v132
	v_mul_f32_e32 v133, v183, v133
	v_mul_f32_e32 v137, v189, v189
	v_mul_f32_e32 v183, v195, v195
	v_fma_f32 v196, v66, v214, v196
	global_store_dwordx4 v[208:209], v[200:203], off
	v_cvt_pk_bf16_f32 v184, v192, v189
	v_cvt_pk_bf16_f32 v185, v136, v195
	v_cvt_pk_bf16_f32 v186, v196, v131
	v_fmac_f32_e32 v137, v192, v192
	v_fmac_f32_e32 v183, v136, v136
	v_mul_f32_e32 v131, v131, v131
	v_fmac_f32_e32 v199, v69, v133
	v_add_f32_e32 v136, v137, v183
	v_fmac_f32_e32 v131, v196, v196
	v_fma_f32 v132, v68, v132, v198
	v_add_f32_e32 v131, v136, v131
	v_mul_f32_e32 v136, v199, v199
	v_fmac_f32_e32 v136, v132, v132
	v_cvt_pk_bf16_f32 v187, v132, v199
	v_add_f32_e32 v131, v136, v131
	v_and_b32_e32 v132, 64, v181
	v_add_f32_e32 v183, v188, v131
	v_xor_b32_e32 v131, 16, v181
	v_add_u32_e32 v190, 64, v132
	v_cmp_lt_i32_e32 vcc, v131, v190
	v_add_u32_e32 v133, 0x80, v204
	s_nop 0
	v_cndmask_b32_e32 v131, v181, v131, vcc
	v_lshlrev_b32_e32 v132, 2, v131
	ds_bpermute_b32 v191, v132, v183
	v_ashrrev_i32_e32 v131, 6, v133
	v_xor_b32_e32 v133, 32, v181
	v_add_u32_e32 v136, v131, v218
	v_cmp_lt_i32_e32 vcc, v133, v190
	v_ashrrev_i32_e32 v137, 31, v136
	v_lshlrev_b64 v[188:189], 15, v[136:137]
	v_cndmask_b32_e32 v133, v181, v133, vcc
	s_waitcnt lgkmcnt(0)
	v_add_f32_e32 v136, v183, v191
	v_lshlrev_b32_e32 v133, 2, v133
	ds_bpermute_b32 v137, v133, v136
	v_lshl_add_u64 v[188:189], s[72:73], 0, v[188:189]
	v_lshl_add_u64 v[188:189], v[188:189], 0, v[206:207]
	v_lshl_add_u64 v[188:189], v[188:189], 0, v[162:163]
	global_store_dwordx4 v[188:189], v[184:187], off
	s_and_saveexec_b64 s[20:21], s[2:3]
	s_cbranch_execz .LBB0_4173
	s_waitcnt lgkmcnt(0)
	v_add_f32_e32 v136, v136, v137
	v_mul_f32_e32 v136, 0x4f800000, v136
	v_trunc_f32_e32 v136, v136
	v_mul_f32_e32 v137, 0x2f800000, v136
	v_floor_f32_e32 v137, v137
	v_fmac_f32_e32 v136, 0xcf800000, v137
	v_cvt_u32_f32_e32 v136, v136
	v_cvt_u32_f32_e32 v137, v137
	v_lshl_add_u64 v[184:185], v[174:175], 3, s[12:13]
	global_atomic_add_x2 v[184:185], v[136:137], off
